# MLA: O rescale gathered into one block of plain v_mul_f32, skipped when no lane's running max moved
# speedup vs baseline: 1.0388x; 1.0004x over previous
; DI void attn_mla128(KP P, char* lds, bool sample, int b, int h, int ublk) {
;     ...
;             float mx = S[0][0];
; #pragma unroll
;             for (int blk = 0; blk < 4; ++blk)
; #pragma unroll
;                 for (int i = 0; i < 16; ++i) mx = fmaxf(mx, S[blk][i]);
;             mx = fmaxf(mx, __shfl_xor(mx, 32));
;             const float mnew = fmaxf(mrun, mx);
;             const float alpha = __builtin_amdgcn_exp2f(mrun - mnew);
;             mrun = mnew;
;             float ps = 0.f;
; #pragma unroll
;             for (int blk = 0; blk < 4; ++blk)
; #pragma unroll
;                 for (int i = 0; i < 16; ++i) { S[blk][i] = __builtin_amdgcn_exp2f(S[blk][i] - mnew); ps += S[blk][i]; }
;             lrun = lrun * alpha + ps;
; #pragma unroll
;             for (int i = 0; i < 16; ++i) { O0[i] *= alpha; O1[i] *= alpha; }
.LBB0_1231:
	s_or_b64 exec, exec, s[14:15]
	v_max_f32_e32 v169, v81, v81
	v_max_f32_e32 v171, v80, v80
	v_max_f32_e32 v169, v171, v169
	v_max3_f32 v169, v169, v82, v83
	v_max3_f32 v169, v169, v84, v85
	v_max3_f32 v169, v169, v86, v87
	v_max3_f32 v169, v169, v88, v89
	v_max3_f32 v169, v169, v90, v91
	v_max3_f32 v169, v169, v92, v93
	v_max3_f32 v169, v169, v94, v95
	v_max3_f32 v169, v169, v64, v65
	v_max3_f32 v169, v169, v66, v67
	v_max3_f32 v169, v169, v68, v69
	v_max3_f32 v169, v169, v70, v71
	v_max3_f32 v169, v169, v72, v73
	v_max3_f32 v169, v169, v74, v75
	v_max3_f32 v169, v169, v76, v77
	v_max3_f32 v169, v169, v78, v79
	v_max3_f32 v169, v169, v16, v17
	v_max3_f32 v169, v169, v18, v19
	v_max3_f32 v169, v169, v20, v21
	v_max3_f32 v169, v169, v22, v23
	v_max3_f32 v169, v169, v24, v25
	v_max3_f32 v169, v169, v26, v27
	v_max3_f32 v169, v169, v28, v29
	v_max3_f32 v169, v169, v30, v31
	v_max3_f32 v169, v169, v0, v1
	v_max3_f32 v169, v169, v2, v3
	v_max3_f32 v169, v169, v4, v5
	v_max3_f32 v169, v169, v6, v7
	v_max3_f32 v169, v169, v8, v9
	v_max3_f32 v169, v169, v10, v11
	v_cmp_lt_i32_e32 vcc, v191, v184
	v_max3_f32 v169, v169, v12, v13
	v_max3_f32 v169, v169, v14, v15
	v_cndmask_b32_e32 v171, v183, v191, vcc
	v_lshlrev_b32_e32 v171, 2, v171
	ds_bpermute_b32 v171, v171, v169
	s_waitcnt lgkmcnt(0)
	v_max3_f32 v169, v170, v169, v171
	v_sub_f32_e32 v80, v80, v169
	v_exp_f32_e32 v171, v80
	v_sub_f32_e32 v81, v81, v169
	v_exp_f32_e32 v81, v81
	v_sub_f32_e32 v82, v82, v169
	v_exp_f32_e32 v82, v82
	v_sub_f32_e32 v83, v83, v169
	v_exp_f32_e32 v83, v83
	v_sub_f32_e32 v84, v84, v169
	v_sub_f32_e32 v80, v170, v169
	v_add_f32_e32 v170, 0, v171
	v_exp_f32_e32 v84, v84
	v_sub_f32_e32 v85, v85, v169
	v_add_f32_e32 v170, v81, v170
	v_exp_f32_e32 v85, v85
	v_sub_f32_e32 v86, v86, v169
	v_add_f32_e32 v170, v82, v170
	v_exp_f32_e32 v86, v86
	v_sub_f32_e32 v87, v87, v169
	v_add_f32_e32 v170, v83, v170
	v_exp_f32_e32 v87, v87
	v_sub_f32_e32 v88, v88, v169
	v_add_f32_e32 v170, v84, v170
	v_exp_f32_e32 v88, v88
	v_sub_f32_e32 v89, v89, v169
	v_add_f32_e32 v170, v85, v170
	v_exp_f32_e32 v89, v89
	v_sub_f32_e32 v90, v90, v169
	v_add_f32_e32 v170, v86, v170
	v_exp_f32_e32 v90, v90
	v_sub_f32_e32 v91, v91, v169
	v_add_f32_e32 v170, v87, v170
	v_exp_f32_e32 v91, v91
	v_sub_f32_e32 v92, v92, v169
	v_add_f32_e32 v170, v88, v170
	v_exp_f32_e32 v92, v92
	v_sub_f32_e32 v93, v93, v169
	v_add_f32_e32 v170, v89, v170
	v_exp_f32_e32 v93, v93
	v_sub_f32_e32 v94, v94, v169
	v_add_f32_e32 v170, v90, v170
	v_exp_f32_e32 v94, v94
	v_sub_f32_e32 v95, v95, v169
	v_add_f32_e32 v170, v91, v170
	v_exp_f32_e32 v95, v95
	v_sub_f32_e32 v64, v64, v169
	v_add_f32_e32 v170, v92, v170
	v_exp_f32_e32 v64, v64
	v_sub_f32_e32 v65, v65, v169
	v_add_f32_e32 v170, v93, v170
	v_exp_f32_e32 v65, v65
	v_sub_f32_e32 v66, v66, v169
	v_add_f32_e32 v170, v94, v170
	v_exp_f32_e32 v66, v66
	v_sub_f32_e32 v67, v67, v169
	v_add_f32_e32 v170, v95, v170
	v_exp_f32_e32 v67, v67
	v_sub_f32_e32 v68, v68, v169
	v_add_f32_e32 v170, v64, v170
	v_exp_f32_e32 v68, v68
	v_sub_f32_e32 v69, v69, v169
	v_add_f32_e32 v170, v65, v170
	v_exp_f32_e32 v69, v69
	v_sub_f32_e32 v70, v70, v169
	v_add_f32_e32 v170, v66, v170
	v_exp_f32_e32 v70, v70
	v_sub_f32_e32 v71, v71, v169
	v_add_f32_e32 v170, v67, v170
	v_exp_f32_e32 v71, v71
	v_sub_f32_e32 v72, v72, v169
	v_add_f32_e32 v170, v68, v170
	v_exp_f32_e32 v72, v72
	v_sub_f32_e32 v73, v73, v169
	v_add_f32_e32 v170, v69, v170
	v_exp_f32_e32 v73, v73
	v_sub_f32_e32 v74, v74, v169
	v_add_f32_e32 v170, v70, v170
	v_exp_f32_e32 v74, v74
	v_sub_f32_e32 v75, v75, v169
	v_add_f32_e32 v170, v71, v170
	v_exp_f32_e32 v75, v75
	v_sub_f32_e32 v76, v76, v169
	v_add_f32_e32 v170, v72, v170
	v_exp_f32_e32 v76, v76
	v_sub_f32_e32 v77, v77, v169
	v_add_f32_e32 v170, v73, v170
	v_exp_f32_e32 v77, v77
	v_sub_f32_e32 v78, v78, v169
	v_add_f32_e32 v170, v74, v170
	v_exp_f32_e32 v78, v78
	v_sub_f32_e32 v79, v79, v169
	v_add_f32_e32 v170, v75, v170
	v_exp_f32_e32 v79, v79
	v_sub_f32_e32 v16, v16, v169
	v_add_f32_e32 v170, v76, v170
	v_exp_f32_e32 v172, v16
	v_sub_f32_e32 v17, v17, v169
	v_add_f32_e32 v16, v77, v170
	v_exp_f32_e32 v170, v17
	v_sub_f32_e32 v17, v18, v169
	v_add_f32_e32 v16, v78, v16
	v_exp_f32_e32 v173, v17
	v_sub_f32_e32 v17, v19, v169
	v_add_f32_e32 v16, v79, v16
	v_exp_f32_e32 v174, v17
	v_sub_f32_e32 v17, v20, v169
	v_add_f32_e32 v16, v172, v16
	v_exp_f32_e32 v175, v17
	v_sub_f32_e32 v17, v21, v169
	v_add_f32_e32 v16, v170, v16
	v_exp_f32_e32 v202, v17
	v_sub_f32_e32 v17, v22, v169
	v_add_f32_e32 v16, v173, v16
	v_exp_f32_e32 v203, v17
	v_sub_f32_e32 v17, v23, v169
	v_add_f32_e32 v16, v174, v16
	v_exp_f32_e32 v204, v17
	v_sub_f32_e32 v17, v24, v169
	v_add_f32_e32 v16, v175, v16
	v_exp_f32_e32 v205, v17
	v_sub_f32_e32 v17, v25, v169
	v_add_f32_e32 v16, v202, v16
	v_exp_f32_e32 v206, v17
	v_sub_f32_e32 v17, v26, v169
	v_add_f32_e32 v16, v203, v16
	v_exp_f32_e32 v207, v17
	v_sub_f32_e32 v17, v27, v169
	v_add_f32_e32 v16, v204, v16
	v_exp_f32_e32 v208, v17
	v_sub_f32_e32 v17, v28, v169
	v_add_f32_e32 v16, v205, v16
	v_exp_f32_e32 v28, v17
	v_add_f32_e32 v16, v206, v16
	v_add_f32_e32 v16, v207, v16
	v_add3_u32 v24, s19, v161, v144
	v_add_f32_e32 v16, v208, v16
	v_add_u32_e32 v210, 0x6800, v24
	v_add_f32_e32 v209, v28, v16
	ds_read_b128 v[16:19], v210
	v_exp_f32_e32 v80, v80
	s_nop 0
	v_cmp_neq_f32_e32 vcc, 1.0, v80
	s_nop 1
	s_cbranch_vccz .Lmla_norescale
	v_mul_f32_e32 v46, v80, v46
	v_mul_f32_e32 v47, v80, v47
	v_mul_f32_e32 v44, v80, v44
	v_mul_f32_e32 v45, v80, v45
	v_mul_f32_e32 v42, v80, v42
	v_mul_f32_e32 v43, v80, v43
	v_mul_f32_e32 v40, v80, v40
	v_mul_f32_e32 v41, v80, v41
	v_mul_f32_e32 v38, v80, v38
	v_mul_f32_e32 v39, v80, v39
	v_mul_f32_e32 v36, v80, v36
	v_mul_f32_e32 v37, v80, v37
	v_mul_f32_e32 v34, v80, v34
	v_mul_f32_e32 v35, v80, v35
	v_mul_f32_e32 v32, v80, v32
	v_mul_f32_e32 v33, v80, v33
	v_mul_f32_e32 v62, v80, v62
	v_mul_f32_e32 v63, v80, v63
	v_mul_f32_e32 v60, v80, v60
	v_mul_f32_e32 v61, v80, v61
	v_mul_f32_e32 v58, v80, v58
	v_mul_f32_e32 v59, v80, v59
	v_mul_f32_e32 v56, v80, v56
	v_mul_f32_e32 v57, v80, v57
	v_mul_f32_e64 v54, v54, v80
	v_mul_f32_e64 v55, v55, v80
	v_mul_f32_e64 v52, v52, v80
	v_mul_f32_e64 v53, v53, v80
	v_mul_f32_e32 v50, v80, v50
	v_mul_f32_e32 v51, v80, v51
	v_mul_f32_e32 v48, v80, v48
	v_mul_f32_e32 v49, v80, v49
; DI unsigned pk2(float a, float b) { f32x2 f = {a, b}; bf2_t r = __builtin_convertvector(f, bf2_t); return __builtin_bit_cast(unsigned, r); }
; #define MFMA32(a, b, c) __builtin_amdgcn_mfma_f32_32x32x16_bf16((a), (b), (c), 0, 0, 0)
; DI void attn_mla128(KP P, char* lds, bool sample, int b, int h, int ublk) {
;     ...
;             float ps = 0.f;
; #pragma unroll
;             for (int blk = 0; blk < 4; ++blk)
; #pragma unroll
;                 for (int i = 0; i < 16; ++i) { S[blk][i] = __builtin_amdgcn_exp2f(S[blk][i] - mnew); ps += S[blk][i]; }
;             lrun = lrun * alpha + ps;
; #pragma unroll
;             for (int i = 0; i < 16; ++i) { O0[i] *= alpha; O1[i] *= alpha; }
; #pragma unroll
;             for (int blk = 0; blk < 4; ++blk)
; #pragma unroll
;                 for (int s = 0; s < 2; ++s) {
;                     u32x4 a;
;                     a.x = pk2(S[blk][8 * s], S[blk][8 * s + 1]); a.y = pk2(S[blk][8 * s + 2], S[blk][8 * s + 3]); a.z = pk2(S[blk][8 * s + 4], S[blk][8 * s + 5]); a.w = pk2(S[blk][8 * s + 6], S[blk][8 * s + 7]);
;                     const bf16x8 pf = __builtin_bit_cast(bf16x8, a);
;                     const int koff = (32 * blk + 16 * s + 4 * hh) * 2;
;                     const s16x4 lo0 = *(const s16x4*)(vb_ + ql * VS + koff), hi0 = *(const s16x4*)(vb_ + ql * VS + koff + 16);
;                     const s16x4 lo1 = *(const s16x4*)(vb_ + (32 + ql) * VS + koff), hi1 = *(const s16x4*)(vb_ + (32 + ql) * VS + koff + 16);
;                     const bf16x8 v0 = __builtin_shufflevector(lo0, hi0, 0, 1, 2, 3, 4, 5, 6, 7), v1 = __builtin_shufflevector(lo1, hi1, 0, 1, 2, 3, 4, 5, 6, 7);
;                     O0 = MFMA32(v0, pf, O0); O1 = MFMA32(v1, pf, O1);
;                 }
.Lmla_norescale:
	v_cvt_pk_bf16_f32 v20, v171, v81
	v_cvt_pk_bf16_f32 v21, v82, v83
	v_cvt_pk_bf16_f32 v22, v84, v85
	v_add_u32_e32 v81, 0x8800, v24
	ds_read_b128 v[24:27], v81 offset:512
	v_cvt_pk_bf16_f32 v23, v86, v87
	s_waitcnt lgkmcnt(1)
	v_mfma_f32_32x32x16_bf16 v[32:47], v[16:19], v[20:23], v[32:47]
	ds_read_b128 v[16:19], v210 offset:32
	v_sub_f32_e32 v0, v0, v169
	v_sub_f32_e32 v4, v4, v169
	s_waitcnt lgkmcnt(1)
	v_mfma_f32_32x32x16_bf16 v[48:63], v[24:27], v[20:23], v[48:63]
	v_sub_f32_e32 v20, v29, v169
	v_exp_f32_e32 v29, v20
	v_cvt_pk_bf16_f32 v20, v88, v89
	v_cvt_pk_bf16_f32 v21, v90, v91
	v_cvt_pk_bf16_f32 v22, v92, v93
	v_cvt_pk_bf16_f32 v23, v94, v95
	ds_read_b128 v[24:27], v81 offset:544
	v_sub_f32_e32 v8, v8, v169
	s_waitcnt lgkmcnt(1)
	v_mfma_f32_32x32x16_bf16 v[32:47], v[16:19], v[20:23], v[32:47]
	v_sub_f32_e32 v16, v30, v169
	v_exp_f32_e32 v30, v16
	v_add_f32_e32 v16, v29, v209
	v_sub_f32_e32 v17, v31, v169
	v_exp_f32_e32 v31, v17
	v_add_f32_e32 v82, v30, v16
	ds_read_b128 v[16:19], v210 offset:64
	s_waitcnt lgkmcnt(1)
	v_mfma_f32_32x32x16_bf16 v[48:63], v[24:27], v[20:23], v[48:63]
	v_cvt_pk_bf16_f32 v20, v64, v65
	v_exp_f32_e32 v64, v0
	v_sub_f32_e32 v0, v1, v169
	v_cvt_pk_bf16_f32 v21, v66, v67
	v_cvt_pk_bf16_f32 v22, v68, v69
	v_cvt_pk_bf16_f32 v23, v70, v71
	ds_read_b128 v[24:27], v81 offset:576
	v_exp_f32_e32 v65, v0
	v_sub_f32_e32 v0, v2, v169
	s_waitcnt lgkmcnt(1)
	v_mfma_f32_32x32x16_bf16 v[32:47], v[16:19], v[20:23], v[32:47]
	v_exp_f32_e32 v66, v0
	v_sub_f32_e32 v16, v3, v169
	ds_read_b128 v[0:3], v210 offset:96
	v_cvt_pk_bf16_f32 v17, v74, v75
	v_cvt_pk_bf16_f32 v18, v76, v77
	v_cvt_pk_bf16_f32 v19, v78, v79
	v_add_f32_e32 v82, v31, v82
	s_waitcnt lgkmcnt(1)
	v_mfma_f32_32x32x16_bf16 v[48:63], v[24:27], v[20:23], v[48:63]
	v_exp_f32_e32 v24, v16
	v_cvt_pk_bf16_f32 v16, v72, v73
	ds_read_b128 v[20:23], v81 offset:608
	v_exp_f32_e32 v25, v4
	v_sub_f32_e32 v4, v7, v169
	v_cvt_pk_bf16_f32 v7, v203, v204
	v_sub_f32_e32 v12, v12, v169
	s_waitcnt lgkmcnt(1)
	v_mfma_f32_32x32x16_bf16 v[32:47], v[0:3], v[16:19], v[32:47]
	v_sub_f32_e32 v0, v5, v169
	v_exp_f32_e32 v26, v0
	v_sub_f32_e32 v0, v6, v169
	v_exp_f32_e32 v27, v0
	ds_read_b128 v[0:3], v210 offset:128
	v_cvt_pk_bf16_f32 v5, v173, v174
	v_cvt_pk_bf16_f32 v6, v175, v202
	s_waitcnt lgkmcnt(1)
	v_mfma_f32_32x32x16_bf16 v[48:63], v[20:23], v[16:19], v[48:63]
	v_exp_f32_e32 v20, v4
	v_cvt_pk_bf16_f32 v4, v172, v170
	ds_read_b128 v[16:19], v81 offset:640
	v_exp_f32_e32 v21, v8
	v_sub_f32_e32 v8, v11, v169
	v_sub_f32_e32 v15, v15, v169
	v_exp_f32_e32 v12, v12
	s_waitcnt lgkmcnt(1)
	v_mfma_f32_32x32x16_bf16 v[32:47], v[0:3], v[4:7], v[32:47]
	v_sub_f32_e32 v0, v9, v169
	v_exp_f32_e32 v22, v0
	v_sub_f32_e32 v0, v10, v169
	v_exp_f32_e32 v23, v0
	ds_read_b128 v[0:3], v210 offset:160
	v_exp_f32_e32 v15, v15
	v_mov_b32_e32 v170, v169
	s_waitcnt lgkmcnt(1)
	v_mfma_f32_32x32x16_bf16 v[48:63], v[16:19], v[4:7], v[48:63]
	v_exp_f32_e32 v16, v8
	v_cvt_pk_bf16_f32 v4, v205, v206
	v_cvt_pk_bf16_f32 v5, v207, v208
	v_cvt_pk_bf16_f32 v6, v28, v29
	v_cvt_pk_bf16_f32 v7, v30, v31
	ds_read_b128 v[8:11], v81 offset:672
	v_add_f32_e32 v17, v64, v82
	s_waitcnt lgkmcnt(1)
	v_mfma_f32_32x32x16_bf16 v[32:47], v[0:3], v[4:7], v[32:47]
	v_sub_f32_e32 v0, v13, v169
	v_exp_f32_e32 v13, v0
	v_sub_f32_e32 v0, v14, v169
	v_exp_f32_e32 v14, v0
	ds_read_b128 v[0:3], v210 offset:192
	s_waitcnt lgkmcnt(1)
	v_mfma_f32_32x32x16_bf16 v[48:63], v[8:11], v[4:7], v[48:63]
	ds_read_b128 v[8:11], v81 offset:704
	v_cvt_pk_bf16_f32 v4, v64, v65
	v_cvt_pk_bf16_f32 v5, v66, v24
	v_cvt_pk_bf16_f32 v6, v25, v26
	v_cvt_pk_bf16_f32 v7, v27, v20
	s_waitcnt lgkmcnt(1)
	s_nop 0
	v_mfma_f32_32x32x16_bf16 v[32:47], v[0:3], v[4:7], v[32:47]
	v_add_f32_e32 v0, v65, v17
	v_add_f32_e32 v0, v66, v0
	v_add_f32_e32 v0, v24, v0
	v_add_f32_e32 v0, v25, v0
	v_add_f32_e32 v0, v26, v0
	v_add_f32_e32 v17, v27, v0
	ds_read_b128 v[0:3], v210 offset:224
	s_waitcnt lgkmcnt(1)
	v_mfma_f32_32x32x16_bf16 v[48:63], v[8:11], v[4:7], v[48:63]
	ds_read_b128 v[8:11], v81 offset:736
	v_add_f32_e32 v4, v20, v17
	v_add_f32_e32 v17, v21, v4
	v_cvt_pk_bf16_f32 v4, v21, v22
	v_cvt_pk_bf16_f32 v5, v23, v16
	v_cvt_pk_bf16_f32 v6, v12, v13
	v_cvt_pk_bf16_f32 v7, v14, v15
	s_waitcnt lgkmcnt(1)
	s_nop 0
	v_mfma_f32_32x32x16_bf16 v[32:47], v[0:3], v[4:7], v[32:47]
	v_add_f32_e32 v0, v22, v17
	v_add_f32_e32 v0, v23, v0
	v_add_f32_e32 v0, v16, v0
	v_add_f32_e32 v0, v12, v0
	v_add_f32_e32 v0, v13, v0
	v_add_f32_e32 v0, v14, v0
	v_add_f32_e32 v0, v15, v0
	s_waitcnt lgkmcnt(0)
	v_mfma_f32_32x32x16_bf16 v[48:63], v[8:11], v[4:7], v[48:63]
	v_fmac_f32_e32 v0, v149, v80
	v_mov_b32_e32 v149, v0
